# adds: the two grid barriers in front of the 512-row sample rmsnorm phases (P4b, P7) replaced by per-panel completion counters; sample-tile stores device-scope write-through
# baseline (speedup 1.0000x reference)
.LBB0_908:
	v_lshl_add_u64 v[76:77], v[38:39], 0, s[0:1]
	v_add_co_u32_e32 v64, vcc, s22, v76
	v_lshl_add_u64 v[48:49], v[40:41], 0, s[0:1]
	s_nop 0
	v_addc_co_u32_e32 v65, vcc, 0, v77, vcc
	v_add_co_u32_e32 v78, vcc, s23, v76
	s_add_i32 s35, s35, 64
	s_nop 0
	v_addc_co_u32_e32 v79, vcc, 0, v77, vcc
	v_add_co_u32_e32 v80, vcc, s24, v76
	v_lshl_add_u64 v[38:39], v[38:39], 0, s[2:3]
	s_nop 0
	v_addc_co_u32_e32 v81, vcc, 0, v77, vcc
	v_add_co_u32_e32 v66, vcc, s28, v48
	s_cmpk_lt_u32 s35, 0x60
	s_nop 0
	v_addc_co_u32_e32 v67, vcc, 0, v49, vcc
	v_add_co_u32_e32 v72, vcc, s29, v48
	v_lshl_add_u64 v[40:41], v[40:41], 0, s[2:3]
	s_nop 0
	v_addc_co_u32_e32 v73, vcc, 0, v49, vcc
	global_load_dwordx4 v[48:51], v[66:67], off
	global_load_dwordx4 v[52:55], v[64:65], off
	global_load_dwordx4 v[56:59], v[64:65], off offset:64
	global_load_dwordx4 v[60:63], v[66:67], off offset:64
	s_nop 0
	global_load_dwordx4 v[64:67], v[72:73], off
	global_load_dwordx4 v[68:71], v[72:73], off offset:64
	v_add_co_u32_e32 v84, vcc, s25, v76
	s_waitcnt vmcnt(0)
	v_mfma_f32_16x16x32_bf16 v[30:33], v[48:51], v[52:55], v[30:33]
	v_addc_co_u32_e32 v85, vcc, 0, v77, vcc
	v_mfma_f32_16x16x32_bf16 v[26:29], v[64:67], v[52:55], v[26:29]
	global_load_dwordx4 v[52:55], v[78:79], off
	global_load_dwordx4 v[72:75], v[78:79], off offset:64
	v_mfma_f32_16x16x32_bf16 v[30:33], v[60:63], v[56:59], v[30:33]
	v_mfma_f32_16x16x32_bf16 v[26:29], v[68:71], v[56:59], v[26:29]
	s_waitcnt vmcnt(0)
	v_mfma_f32_16x16x32_bf16 v[18:21], v[48:51], v[52:55], v[18:21]
	v_mfma_f32_16x16x32_bf16 v[14:17], v[64:67], v[52:55], v[14:17]
	global_load_dwordx4 v[52:55], v[80:81], off
	global_load_dwordx4 v[76:79], v[80:81], off offset:64
	s_nop 0
	global_load_dwordx4 v[80:83], v[84:85], off
	v_mfma_f32_16x16x32_bf16 v[18:21], v[60:63], v[72:75], v[18:21]
	v_mfma_f32_16x16x32_bf16 v[14:17], v[68:71], v[72:75], v[14:17]
	s_waitcnt vmcnt(0)
	v_mfma_f32_16x16x32_bf16 v[10:13], v[48:51], v[52:55], v[10:13]
	v_mfma_f32_16x16x32_bf16 v[6:9], v[64:67], v[52:55], v[6:9]
	global_load_dwordx4 v[52:55], v[84:85], off offset:64
	v_mfma_f32_16x16x32_bf16 v[2:5], v[48:51], v[80:83], v[2:5]
	v_mfma_f32_16x16x32_bf16 v[22:25], v[64:67], v[80:83], v[22:25]
	v_mfma_f32_16x16x32_bf16 v[10:13], v[60:63], v[76:79], v[10:13]
	v_mfma_f32_16x16x32_bf16 v[6:9], v[68:71], v[76:79], v[6:9]
	s_waitcnt vmcnt(0)
	v_mfma_f32_16x16x32_bf16 v[2:5], v[60:63], v[52:55], v[2:5]
	v_mfma_f32_16x16x32_bf16 v[22:25], v[68:71], v[52:55], v[22:25]
	s_cbranch_scc1 .LBB0_908
	s_lshl_b32 s35, s34, 1
	s_andn2_b32 s35, s35, 63
	s_lshl_b32 s36, s34, 5
	s_waitcnt lgkmcnt(0)
	s_barrier
	ds_write_b128 v46, v[30:33]
	ds_write_b128 v46, v[26:29] offset:64
	ds_write_b128 v46, v[18:21] offset:2048
	ds_write_b128 v46, v[14:17] offset:2112
	ds_write_b128 v46, v[10:13] offset:4096
	ds_write_b128 v46, v[6:9] offset:4160
	ds_write_b128 v46, v[2:5] offset:6144
	ds_write_b128 v46, v[22:25] offset:6208
	v_or_b32_e32 v2, s35, v170
	s_and_b32 s36, s36, 0x3e0
	v_ashrrev_i32_e32 v3, 31, v2
	v_or_b32_e32 v47, s36, v42
	v_lshlrev_b64 v[2:3], 12, v[2:3]
	v_lshl_add_u64 v[2:3], s[54:55], 0, v[2:3]
	v_lshlrev_b32_e32 v34, 2, v47
	v_lshl_add_u64 v[2:3], v[2:3], 0, v[34:35]
	s_waitcnt lgkmcnt(0)
	s_barrier
	global_load_dwordx4 v[2:5], v[2:3], off
	ds_read_b128 v[6:9], v43
	ds_read_b128 v[10:13], v43 offset:8192
	ds_read_b128 v[14:17], v43 offset:16384
	ds_read_b128 v[18:21], v43 offset:24576
	ds_read_b128 v[22:25], v43 offset:32768
	ds_read_b128 v[26:29], v43 offset:40960
	ds_read_b128 v[30:33], v43 offset:49152
	ds_read_b128 v[38:41], v43 offset:57344
	s_waitcnt lgkmcnt(7)
	v_pk_add_f32 v[6:7], v[6:7], 0 op_sel_hi:[1,0]
	v_pk_add_f32 v[8:9], v[8:9], 0 op_sel_hi:[1,0]
	s_waitcnt lgkmcnt(6)
	v_pk_add_f32 v[6:7], v[6:7], v[10:11]
	v_pk_add_f32 v[8:9], v[8:9], v[12:13]
	s_waitcnt lgkmcnt(5)
	v_pk_add_f32 v[6:7], v[6:7], v[14:15]
	s_addk_i32 s35, 0x4000
	v_pk_add_f32 v[8:9], v[8:9], v[16:17]
	s_waitcnt lgkmcnt(4)
	v_pk_add_f32 v[6:7], v[6:7], v[18:19]
	v_or_b32_e32 v48, s35, v170
	v_pk_add_f32 v[8:9], v[8:9], v[20:21]
	s_waitcnt lgkmcnt(3)
	v_pk_add_f32 v[6:7], v[6:7], v[22:23]
	v_ashrrev_i32_e32 v49, 31, v48
	v_pk_add_f32 v[8:9], v[8:9], v[24:25]
	s_waitcnt lgkmcnt(2)
	v_pk_add_f32 v[6:7], v[6:7], v[26:27]
	v_lshlrev_b64 v[48:49], 11, v[48:49]
	v_pk_add_f32 v[8:9], v[8:9], v[28:29]
	s_waitcnt lgkmcnt(1)
	v_pk_add_f32 v[6:7], v[6:7], v[30:31]
	s_add_i32 s34, s34, s90
	s_add_i32 s4, s4, s5
	s_add_i32 s20, s20, s21
	v_lshl_add_u64 v[10:11], s[8:9], 0, v[48:49]
	v_lshlrev_b32_e32 v34, 1, v47
	v_pk_add_f32 v[8:9], v[8:9], v[32:33]
	s_waitcnt lgkmcnt(0)
	v_pk_add_f32 v[6:7], v[6:7], v[38:39]
	v_lshl_add_u64 v[10:11], v[10:11], 0, v[34:35]
	v_pk_add_f32 v[8:9], v[8:9], v[40:41]
	s_cmpk_gt_i32 s34, 0xff
	s_waitcnt vmcnt(0)
	v_pk_add_f32 v[2:3], v[2:3], v[6:7]
	v_pk_add_f32 v[4:5], v[4:5], v[8:9]
	v_cvt_pk_bf16_f32 v2, v2, v3
	s_nop 0
	v_cvt_pk_bf16_f32 v3, v4, v5
	global_store_dwordx2 v[10:11], v[2:3], off sc1
	s_cbranch_scc0 .LBB0_907
.LBB0_910:
	s_waitcnt vmcnt(0)
	s_waitcnt lgkmcnt(0)
	s_barrier
	s_mov_b64 s[0:1], exec
	v_readlane_b32 s2, v254, 2
	v_readlane_b32 s3, v254, 3
	s_and_b64 s[2:3], s[0:1], s[2:3]
	s_mov_b64 exec, s[2:3]
	s_cbranch_execz .LBB0_962
	s_cmp_lg_u32 s90, 0x100
	s_cbranch_scc1 .Lfl7_full
	s_and_b32 s20, s14, 0xff
	s_lshr_b32 s2, s20, 5
	s_lshl_b32 s2, s2, 6
	s_add_i32 s2, s2, 0x3800
	s_add_u32 s2, s74, s2
	s_addc_u32 s3, s75, 0
	v_mov_b32_e32 v2, 0
	v_mov_b32_e32 v3, 1
	s_waitcnt vmcnt(0)
	global_atomic_add v2, v3, s[2:3]
	s_cmp_gt_u32 s20, 63
	s_cbranch_scc1 .LBB0_962
	s_lshr_b32 s4, s20, 3
	s_lshl_b32 s4, s4, 6
	s_add_i32 s4, s4, 0x3800
	s_add_u32 s4, s74, s4
	s_addc_u32 s5, s75, 0
	s_mov_b32 s22, 0
.Lfl7_poll:
	global_load_dword v3, v2, s[4:5] sc1
	s_waitcnt vmcnt(0)
	v_readfirstlane_b32 s23, v3
	s_cmp_ge_u32 s23, 32
	s_cbranch_scc1 .Lfl7_seen
	s_sleep 1
	s_add_i32 s22, s22, 1
	s_cmp_lt_u32 s22, 0x200000
	s_cbranch_scc1 .Lfl7_poll
.Lfl7_seen:
	buffer_inv sc1
	s_waitcnt vmcnt(0)
	s_branch .LBB0_962
.Lfl7_full:
	s_add_i32 s2, 0, 0x21fe0
	v_mov_b32_e32 v2, s2
	s_waitcnt vmcnt(0) expcnt(0) lgkmcnt(0)
	ds_read_b32 v4, v2
	s_add_i32 s2, 0, 0x21fe4
	v_mov_b32_e32 v2, s2
	ds_read_b32 v2, v2
	s_waitcnt lgkmcnt(1)
	v_cmp_ne_u32_e32 vcc, 0, v4
	s_cbranch_vccnz .LBB0_926
	v_readlane_b32 s2, v254, 0
	v_readlane_b32 s3, v254, 1
	s_load_dwordx2 s[20:21], s[2:3], 0x4
	s_add_u32 s2, s74, 0x1000
	s_addc_u32 s3, s75, 0
	s_add_u32 s4, s74, 0x1100
	s_addc_u32 s5, s75, 0
	s_add_u32 s28, s74, 0x1200
	s_addc_u32 s29, s75, 0
	s_waitcnt lgkmcnt(0)
	s_mul_i32 s20, s20, s90
	s_add_u32 s34, s74, 0x1300
	s_mul_i32 s20, s20, s21
	s_addc_u32 s35, s75, 0
	s_mov_b32 s21, 1
	v_mov_b32_e32 v18, 0
	s_branch .LBB0_914

.LBB0_1185:
	s_and_b32 s7, s2, 0xffffffc0
	s_addk_i32 s7, 0x4000
	v_or_b32_e32 v10, s7, v1
	v_mad_i64_i32 v[12:13], s[10:11], v10, s6, v[4:5]
	v_add_co_u32_e32 v14, vcc, 0x16000, v12
	s_and_b32 s0, s4, 0x3e0
	s_nop 0
	v_addc_co_u32_e32 v15, vcc, 0, v13, vcc
	v_or_b32_e32 v2, s0, v1
	v_add_co_u32_e32 v16, vcc, 0x2c000, v12
	v_mul_u32_u24_e32 v2, 0xb00, v2
	s_nop 0
	v_addc_co_u32_e32 v17, vcc, 0, v13, vcc
	v_lshlrev_b32_e32 v2, 1, v2
	v_add_co_u32_e32 v100, vcc, 0x42000, v12
	v_lshl_add_u64 v[10:11], v[6:7], 0, v[2:3]
	s_nop 0
	v_addc_co_u32_e32 v101, vcc, 0, v13, vcc
	v_add_co_u32_e32 v102, vcc, 0x16000, v10
	global_load_dwordx4 v[20:23], v[12:13], off
	global_load_dwordx4 v[24:27], v[12:13], off offset:64
	global_load_dwordx4 v[28:31], v[10:11], off
	global_load_dwordx4 v[32:35], v[12:13], off offset:640
	global_load_dwordx4 v[36:39], v[14:15], off
	global_load_dwordx4 v[40:43], v[14:15], off offset:64
	global_load_dwordx4 v[44:47], v[16:17], off
	global_load_dwordx4 v[52:55], v[14:15], off offset:640
	global_load_dwordx4 v[60:63], v[100:101], off
	v_addc_co_u32_e32 v103, vcc, 0, v11, vcc
	global_load_dwordx4 v[68:71], v[100:101], off offset:64
	global_load_dwordx4 v[72:75], v[102:103], off
	global_load_dwordx4 v[76:79], v[100:101], off offset:640
	s_lshl_b32 s0, s0, 1
	s_add_i32 s14, s14, s90
	s_add_i32 s2, s2, s3
	s_add_i32 s4, s4, s5
	s_cmpk_gt_i32 s14, 0xff
	s_waitcnt vmcnt(0)
	v_mfma_f32_16x16x32_bf16 v[48:51], v[28:31], v[20:23], 0
	v_mfma_f32_16x16x32_bf16 v[56:59], v[28:31], v[36:39], 0
	v_mfma_f32_16x16x32_bf16 v[64:67], v[28:31], v[44:47], 0
	v_mfma_f32_16x16x32_bf16 v[28:31], v[28:31], v[60:63], 0
	v_mfma_f32_16x16x32_bf16 v[20:23], v[72:75], v[20:23], 0
	v_mfma_f32_16x16x32_bf16 v[36:39], v[72:75], v[36:39], 0
	v_mfma_f32_16x16x32_bf16 v[44:47], v[72:75], v[44:47], 0
	v_mfma_f32_16x16x32_bf16 v[60:63], v[72:75], v[60:63], 0
	global_load_dwordx4 v[72:75], v[10:11], off offset:64
	global_load_dwordx4 v[80:83], v[10:11], off offset:128
	global_load_dwordx4 v[84:87], v[16:17], off offset:64
	global_load_dwordx4 v[88:91], v[16:17], off offset:128
	s_waitcnt vmcnt(0)
	v_mfma_f32_16x16x32_bf16 v[48:51], v[72:75], v[24:27], v[48:51]
	v_mfma_f32_16x16x32_bf16 v[56:59], v[72:75], v[40:43], v[56:59]
	v_mfma_f32_16x16x32_bf16 v[64:67], v[72:75], v[84:87], v[64:67]
	v_mfma_f32_16x16x32_bf16 v[28:31], v[72:75], v[68:71], v[28:31]
	global_load_dwordx4 v[72:75], v[102:103], off offset:64
	global_load_dwordx4 v[92:95], v[102:103], off offset:128
	v_mfma_f32_16x16x32_bf16 v[64:67], v[80:83], v[88:91], v[64:67]
	s_waitcnt vmcnt(0)
	v_mfma_f32_16x16x32_bf16 v[20:23], v[72:75], v[24:27], v[20:23]
	v_mfma_f32_16x16x32_bf16 v[24:27], v[72:75], v[40:43], v[36:39]
	v_mfma_f32_16x16x32_bf16 v[36:39], v[72:75], v[84:87], v[44:47]
	v_mfma_f32_16x16x32_bf16 v[40:43], v[72:75], v[68:71], v[60:63]
	s_nop 1
	global_load_dwordx4 v[44:47], v[12:13], off offset:128
	global_load_dwordx4 v[60:63], v[12:13], off offset:192
	global_load_dwordx4 v[68:71], v[14:15], off offset:128
	global_load_dwordx4 v[72:75], v[14:15], off offset:192
	global_load_dwordx4 v[84:87], v[100:101], off offset:128
	global_load_dwordx4 v[96:99], v[100:101], off offset:192
	v_mfma_f32_16x16x32_bf16 v[36:39], v[92:95], v[88:91], v[36:39]
	s_waitcnt vmcnt(0)
	v_mfma_f32_16x16x32_bf16 v[48:51], v[80:83], v[44:47], v[48:51]
	v_mfma_f32_16x16x32_bf16 v[56:59], v[80:83], v[68:71], v[56:59]
	v_mfma_f32_16x16x32_bf16 v[28:31], v[80:83], v[84:87], v[28:31]
	v_mfma_f32_16x16x32_bf16 v[20:23], v[92:95], v[44:47], v[20:23]
	v_mfma_f32_16x16x32_bf16 v[24:27], v[92:95], v[68:71], v[24:27]
	global_load_dwordx4 v[44:47], v[10:11], off offset:192
	global_load_dwordx4 v[68:71], v[10:11], off offset:256
	v_mfma_f32_16x16x32_bf16 v[40:43], v[92:95], v[84:87], v[40:43]
	global_load_dwordx4 v[80:83], v[16:17], off offset:192
	global_load_dwordx4 v[84:87], v[16:17], off offset:256
	s_waitcnt vmcnt(0)
	v_mfma_f32_16x16x32_bf16 v[48:51], v[44:47], v[60:63], v[48:51]
	v_mfma_f32_16x16x32_bf16 v[56:59], v[44:47], v[72:75], v[56:59]
	v_mfma_f32_16x16x32_bf16 v[64:67], v[44:47], v[80:83], v[64:67]
	v_mfma_f32_16x16x32_bf16 v[28:31], v[44:47], v[96:99], v[28:31]
	global_load_dwordx4 v[44:47], v[102:103], off offset:192
	global_load_dwordx4 v[88:91], v[102:103], off offset:256
	s_waitcnt vmcnt(0)
	v_mfma_f32_16x16x32_bf16 v[20:23], v[44:47], v[60:63], v[20:23]
	v_mfma_f32_16x16x32_bf16 v[24:27], v[44:47], v[72:75], v[24:27]
	v_mfma_f32_16x16x32_bf16 v[36:39], v[44:47], v[80:83], v[36:39]
	v_mfma_f32_16x16x32_bf16 v[40:43], v[44:47], v[96:99], v[40:43]
	global_load_dwordx4 v[44:47], v[12:13], off offset:256
	global_load_dwordx4 v[60:63], v[12:13], off offset:320
	global_load_dwordx4 v[72:75], v[14:15], off offset:256
	global_load_dwordx4 v[80:83], v[14:15], off offset:320
	global_load_dwordx4 v[92:95], v[100:101], off offset:256
	global_load_dwordx4 v[96:99], v[100:101], off offset:320
	s_waitcnt vmcnt(0)
	v_mfma_f32_16x16x32_bf16 v[48:51], v[68:71], v[44:47], v[48:51]
	v_mfma_f32_16x16x32_bf16 v[56:59], v[68:71], v[72:75], v[56:59]
	v_mfma_f32_16x16x32_bf16 v[64:67], v[68:71], v[84:87], v[64:67]
	v_mfma_f32_16x16x32_bf16 v[28:31], v[68:71], v[92:95], v[28:31]
	v_mfma_f32_16x16x32_bf16 v[20:23], v[88:91], v[44:47], v[20:23]
	global_load_dwordx4 v[44:47], v[10:11], off offset:320
	global_load_dwordx4 v[68:71], v[10:11], off offset:384
	v_mfma_f32_16x16x32_bf16 v[24:27], v[88:91], v[72:75], v[24:27]
	v_mfma_f32_16x16x32_bf16 v[36:39], v[88:91], v[84:87], v[36:39]
	global_load_dwordx4 v[72:75], v[16:17], off offset:320
	global_load_dwordx4 v[84:87], v[16:17], off offset:384
	v_mfma_f32_16x16x32_bf16 v[40:43], v[88:91], v[92:95], v[40:43]
	s_waitcnt vmcnt(0)
	v_mfma_f32_16x16x32_bf16 v[48:51], v[44:47], v[60:63], v[48:51]
	v_mfma_f32_16x16x32_bf16 v[56:59], v[44:47], v[80:83], v[56:59]
	v_mfma_f32_16x16x32_bf16 v[64:67], v[44:47], v[72:75], v[64:67]
	v_mfma_f32_16x16x32_bf16 v[28:31], v[44:47], v[96:99], v[28:31]
	global_load_dwordx4 v[44:47], v[102:103], off offset:320
	global_load_dwordx4 v[88:91], v[102:103], off offset:384
	s_waitcnt vmcnt(0)
	v_mfma_f32_16x16x32_bf16 v[20:23], v[44:47], v[60:63], v[20:23]
	v_mfma_f32_16x16x32_bf16 v[24:27], v[44:47], v[80:83], v[24:27]
	v_mfma_f32_16x16x32_bf16 v[36:39], v[44:47], v[72:75], v[36:39]
	v_mfma_f32_16x16x32_bf16 v[40:43], v[44:47], v[96:99], v[40:43]
	global_load_dwordx4 v[44:47], v[12:13], off offset:384
	global_load_dwordx4 v[60:63], v[12:13], off offset:448
	global_load_dwordx4 v[72:75], v[14:15], off offset:384
	global_load_dwordx4 v[80:83], v[14:15], off offset:448
	global_load_dwordx4 v[92:95], v[100:101], off offset:384
	global_load_dwordx4 v[96:99], v[100:101], off offset:448
	s_waitcnt vmcnt(0)
	v_mfma_f32_16x16x32_bf16 v[48:51], v[68:71], v[44:47], v[48:51]
	v_mfma_f32_16x16x32_bf16 v[56:59], v[68:71], v[72:75], v[56:59]
	v_mfma_f32_16x16x32_bf16 v[64:67], v[68:71], v[84:87], v[64:67]
	v_mfma_f32_16x16x32_bf16 v[28:31], v[68:71], v[92:95], v[28:31]
	v_mfma_f32_16x16x32_bf16 v[20:23], v[88:91], v[44:47], v[20:23]
	global_load_dwordx4 v[44:47], v[10:11], off offset:448
	global_load_dwordx4 v[68:71], v[10:11], off offset:512
	v_mfma_f32_16x16x32_bf16 v[24:27], v[88:91], v[72:75], v[24:27]
	v_mfma_f32_16x16x32_bf16 v[36:39], v[88:91], v[84:87], v[36:39]
	global_load_dwordx4 v[72:75], v[16:17], off offset:448
	global_load_dwordx4 v[84:87], v[16:17], off offset:512
	v_mfma_f32_16x16x32_bf16 v[40:43], v[88:91], v[92:95], v[40:43]
	s_waitcnt vmcnt(0)
	v_mfma_f32_16x16x32_bf16 v[48:51], v[44:47], v[60:63], v[48:51]
	v_mfma_f32_16x16x32_bf16 v[56:59], v[44:47], v[80:83], v[56:59]
	v_mfma_f32_16x16x32_bf16 v[64:67], v[44:47], v[72:75], v[64:67]
	v_mfma_f32_16x16x32_bf16 v[28:31], v[44:47], v[96:99], v[28:31]
	global_load_dwordx4 v[44:47], v[102:103], off offset:448
	global_load_dwordx4 v[88:91], v[102:103], off offset:512
	s_waitcnt vmcnt(0)
	v_mfma_f32_16x16x32_bf16 v[20:23], v[44:47], v[60:63], v[20:23]
	v_mfma_f32_16x16x32_bf16 v[24:27], v[44:47], v[80:83], v[24:27]
	v_mfma_f32_16x16x32_bf16 v[36:39], v[44:47], v[72:75], v[36:39]
	v_mfma_f32_16x16x32_bf16 v[40:43], v[44:47], v[96:99], v[40:43]
	global_load_dwordx4 v[44:47], v[12:13], off offset:512
	global_load_dwordx4 v[60:63], v[12:13], off offset:576
	global_load_dwordx4 v[72:75], v[14:15], off offset:512
	global_load_dwordx4 v[80:83], v[14:15], off offset:576
	s_waitcnt vmcnt(0)
	v_mfma_f32_16x16x32_bf16 v[12:15], v[68:71], v[72:75], v[56:59]
	v_mfma_f32_16x16x32_bf16 v[56:59], v[68:71], v[84:87], v[64:67]
	s_nop 2
	global_load_dwordx4 v[64:67], v[100:101], off offset:512
	global_load_dwordx4 v[92:95], v[100:101], off offset:576
	v_mfma_f32_16x16x32_bf16 v[48:51], v[68:71], v[44:47], v[48:51]
	s_waitcnt vmcnt(0)
	v_mfma_f32_16x16x32_bf16 v[28:31], v[68:71], v[64:67], v[28:31]
	v_mfma_f32_16x16x32_bf16 v[20:23], v[88:91], v[44:47], v[20:23]
	v_mfma_f32_16x16x32_bf16 v[24:27], v[88:91], v[72:75], v[24:27]
	v_mfma_f32_16x16x32_bf16 v[40:43], v[88:91], v[64:67], v[40:43]
	global_load_dwordx4 v[44:47], v[10:11], off offset:576
	global_load_dwordx4 v[64:67], v[10:11], off offset:640
	global_load_dwordx4 v[68:71], v[16:17], off offset:576
	global_load_dwordx4 v[72:75], v[16:17], off offset:640
	s_waitcnt vmcnt(0)
	v_mfma_f32_16x16x32_bf16 v[10:13], v[44:47], v[80:83], v[12:15]
	v_mfma_f32_16x16x32_bf16 v[14:17], v[44:47], v[68:71], v[56:59]
	s_nop 2
	global_load_dwordx4 v[56:59], v[102:103], off offset:576
	v_mfma_f32_16x16x32_bf16 v[48:51], v[44:47], v[60:63], v[48:51]
	v_mfma_f32_16x16x32_bf16 v[28:31], v[44:47], v[92:95], v[28:31]
	global_load_dwordx4 v[44:47], v[102:103], off offset:640
	s_waitcnt lgkmcnt(0)
	s_barrier
	v_mfma_f32_16x16x32_bf16 v[36:39], v[88:91], v[84:87], v[36:39]
	s_waitcnt vmcnt(1)
	v_mfma_f32_16x16x32_bf16 v[20:23], v[56:59], v[60:63], v[20:23]
	v_mfma_f32_16x16x32_bf16 v[24:27], v[56:59], v[80:83], v[24:27]
	v_mfma_f32_16x16x32_bf16 v[36:39], v[56:59], v[68:71], v[36:39]
	v_mfma_f32_16x16x32_bf16 v[40:43], v[56:59], v[92:95], v[40:43]
	v_or_b32_e32 v56, s7, v170
	v_ashrrev_i32_e32 v57, 31, v56
	v_lshlrev_b64 v[56:57], 11, v[56:57]
	v_mfma_f32_16x16x32_bf16 v[48:51], v[64:67], v[32:35], v[48:51]
	v_lshl_add_u64 v[56:57], s[8:9], 0, v[56:57]
	v_mfma_f32_16x16x32_bf16 v[10:13], v[64:67], v[52:55], v[10:13]
	v_mfma_f32_16x16x32_bf16 v[14:17], v[64:67], v[72:75], v[14:17]
	s_nop 4
	ds_write_b128 v19, v[48:51]
	s_waitcnt vmcnt(0)
	v_mfma_f32_16x16x32_bf16 v[20:23], v[44:47], v[32:35], v[20:23]
	v_lshl_add_u64 v[32:33], v[56:57], 0, s[0:1]
	v_lshl_add_u64 v[56:57], v[32:33], 0, v[8:9]
	v_mfma_f32_16x16x32_bf16 v[28:31], v[64:67], v[76:79], v[28:31]
	ds_write_b128 v19, v[10:13] offset:2048
	ds_write_b128 v19, v[14:17] offset:4096
	s_nop 5
	ds_write_b128 v19, v[28:31] offset:6144
	v_mfma_f32_16x16x32_bf16 v[24:27], v[44:47], v[52:55], v[24:27]
	v_mfma_f32_16x16x32_bf16 v[32:35], v[44:47], v[72:75], v[36:39]
	v_mfma_f32_16x16x32_bf16 v[10:13], v[44:47], v[76:79], v[40:43]
	ds_write_b128 v19, v[20:23] offset:64
	s_nop 4
	ds_write_b128 v19, v[24:27] offset:2112
	ds_write_b128 v19, v[32:35] offset:4160
	ds_write_b128 v19, v[10:13] offset:6208
	s_waitcnt lgkmcnt(0)
	s_barrier
	global_load_dwordx2 v[44:45], v[56:57], off
	ds_read_b128 v[10:13], v18
	ds_read_b128 v[14:17], v18 offset:8192
	ds_read_b128 v[20:23], v18 offset:16384
	ds_read_b128 v[24:27], v18 offset:24576
	ds_read_b128 v[28:31], v18 offset:32768
	ds_read_b128 v[32:35], v18 offset:40960
	ds_read_b128 v[36:39], v18 offset:49152
	ds_read_b128 v[40:43], v18 offset:57344
	s_waitcnt lgkmcnt(7)
	v_pk_add_f32 v[12:13], v[12:13], 0 op_sel_hi:[1,0]
	v_pk_add_f32 v[10:11], v[10:11], 0 op_sel_hi:[1,0]
	s_waitcnt lgkmcnt(6)
	v_pk_add_f32 v[12:13], v[12:13], v[16:17]
	v_pk_add_f32 v[10:11], v[10:11], v[14:15]
	s_waitcnt lgkmcnt(5)
	v_pk_add_f32 v[12:13], v[12:13], v[22:23]
	v_pk_add_f32 v[10:11], v[10:11], v[20:21]
	s_waitcnt lgkmcnt(4)
	v_pk_add_f32 v[12:13], v[12:13], v[26:27]
	v_pk_add_f32 v[10:11], v[10:11], v[24:25]
	s_waitcnt lgkmcnt(3)
	v_pk_add_f32 v[12:13], v[12:13], v[30:31]
	v_pk_add_f32 v[10:11], v[10:11], v[28:29]
	s_waitcnt lgkmcnt(2)
	v_pk_add_f32 v[12:13], v[12:13], v[34:35]
	v_pk_add_f32 v[10:11], v[10:11], v[32:33]
	s_waitcnt lgkmcnt(1)
	v_pk_add_f32 v[12:13], v[12:13], v[38:39]
	v_pk_add_f32 v[10:11], v[10:11], v[36:37]
	s_waitcnt lgkmcnt(0)
	v_pk_add_f32 v[12:13], v[12:13], v[42:43]
	v_pk_add_f32 v[10:11], v[10:11], v[40:41]
	s_waitcnt vmcnt(0)
	v_lshlrev_b32_e32 v2, 16, v44
	v_and_b32_e32 v14, 0xffff0000, v44
	v_lshlrev_b32_e32 v15, 16, v45
	v_and_b32_e32 v16, 0xffff0000, v45
	v_add_f32_e32 v2, v10, v2
	v_add_f32_e32 v10, v11, v14
	v_add_f32_e32 v11, v12, v15
	v_add_f32_e32 v12, v13, v16
	v_cvt_pk_bf16_f32 v10, v2, v10
	v_cvt_pk_bf16_f32 v11, v11, v12
	global_store_dwordx2 v[56:57], v[10:11], off sc1
	s_cbranch_scc0 .LBB0_1185

.Lfl10_poll:
	global_load_dword v3, v2, s[4:5] sc1
	s_waitcnt vmcnt(0)
	v_readfirstlane_b32 s23, v3
	s_cmp_ge_u32 s23, 64
	s_cbranch_scc1 .Lfl10_seen
	s_sleep 1
	s_add_i32 s22, s22, 1
	s_cmp_lt_u32 s22, 0x200000
	s_cbranch_scc1 .Lfl10_poll

.Lfl10_full:
	s_add_i32 s2, 0, 0x21fe0
	v_mov_b32_e32 v1, s2
	s_waitcnt vmcnt(0) expcnt(0) lgkmcnt(0)
	ds_read_b32 v3, v1
	s_add_i32 s2, 0, 0x21fe4
	v_mov_b32_e32 v1, s2
	ds_read_b32 v1, v1
	s_waitcnt lgkmcnt(1)
	v_cmp_ne_u32_e32 vcc, 0, v3
	s_cbranch_vccnz .LBB0_1202
	v_readlane_b32 s2, v254, 0
	v_readlane_b32 s3, v254, 1
	s_load_dwordx2 s[6:7], s[2:3], 0x4
	s_add_u32 s2, s74, 0x1000
	s_addc_u32 s3, s75, 0
	s_add_u32 s4, s74, 0x1100
	s_addc_u32 s5, s75, 0
	s_waitcnt lgkmcnt(0)
	s_mul_i32 s20, s6, s90
	s_add_u32 s6, s74, 0x1200
	s_mul_i32 s20, s20, s7
	s_addc_u32 s7, s75, 0
	s_add_u32 s10, s74, 0x1300
	s_addc_u32 s11, s75, 0
	s_mov_b32 s21, 1
	v_mov_b32_e32 v17, 0
	s_branch .LBB0_1190
